# stack18 + grid barrier: local workgroups poll the cross-XCD release word directly instead of the per-XCD forwarded one
# speedup vs baseline: 1.0060x; 1.0060x over previous
.LBB0_60:
	s_or_b64 exec, exec, s[12:13]
	v_cvt_f32_u32_e32 v4, v2
	s_waitcnt vmcnt(0)
	v_readfirstlane_b32 s10, v3
	v_sub_u32_e32 v3, 0, v2
	v_rcp_iflag_f32_e32 v4, v4
	v_add_u32_e32 v5, s10, v1
	v_mul_f32_e32 v4, 0x4f7ffffe, v4
	v_cvt_u32_f32_e32 v4, v4
	v_mul_lo_u32 v1, v3, v4
	v_mul_hi_u32 v1, v4, v1
	v_add_u32_e32 v1, v4, v1
	v_mul_hi_u32 v1, v5, v1
	v_mul_lo_u32 v3, v1, v2
	v_sub_u32_e32 v3, v5, v3
	v_add_u32_e32 v4, 1, v1
	v_cmp_ge_u32_e32 vcc, v3, v2
	s_nop 1
	v_cndmask_b32_e32 v1, v1, v4, vcc
	v_sub_u32_e32 v4, v3, v2
	v_cndmask_b32_e32 v3, v3, v4, vcc
	v_add_u32_e32 v4, 1, v1
	v_cmp_ge_u32_e32 vcc, v3, v2
	v_add_u32_e32 v3, 1, v5
	s_nop 0
	v_cndmask_b32_e32 v1, v1, v4, vcc
	v_mul_lo_u32 v4, v2, v1
	v_add_u32_e32 v2, v4, v2
	v_cmp_ne_u32_e32 vcc, v3, v2
	s_and_saveexec_b64 s[10:11], vcc
	s_xor_b64 s[10:11], exec, s[10:11]
	s_cbranch_execz .LBB0_74
	s_movk_i32 s12, 0xd40
	s_mov_b32 s13, 0
	s_lshl_b64 s[12:13], s[12:13], 2
	s_add_u32 s16, s2, s12
	s_addc_u32 s17, s3, s13
	s_waitcnt lgkmcnt(0)
	v_mov_b32_e32 v0, 0
	global_load_dword v2, v0, s[16:17] sc1
	s_waitcnt vmcnt(0)
	v_cmp_eq_u32_e32 vcc, v2, v1
	s_and_saveexec_b64 s[12:13], vcc
	s_cbranch_execz .LBB0_73
	s_add_u32 s14, s8, 0x80200
	s_addc_u32 s15, s9, 0
	s_mov_b32 s28, 1
	s_mov_b64 s[18:19], 0
	s_branch .LBB0_64

.LBB0_272:
	s_or_b64 exec, exec, s[18:19]
	v_cvt_f32_u32_e32 v5, v3
	s_waitcnt vmcnt(0)
	v_readfirstlane_b32 s13, v4
	v_sub_u32_e32 v4, 0, v3
	v_rcp_iflag_f32_e32 v5, v5
	v_add_u32_e32 v6, s13, v0
	v_mul_f32_e32 v5, 0x4f7ffffe, v5
	v_cvt_u32_f32_e32 v5, v5
	v_mul_lo_u32 v0, v4, v5
	v_mul_hi_u32 v0, v5, v0
	v_add_u32_e32 v0, v5, v0
	v_mul_hi_u32 v0, v6, v0
	v_mul_lo_u32 v4, v0, v3
	v_sub_u32_e32 v4, v6, v4
	v_add_u32_e32 v5, 1, v0
	v_cmp_ge_u32_e32 vcc, v4, v3
	s_nop 1
	v_cndmask_b32_e32 v0, v0, v5, vcc
	v_sub_u32_e32 v5, v4, v3
	v_cndmask_b32_e32 v4, v4, v5, vcc
	v_add_u32_e32 v5, 1, v0
	v_cmp_ge_u32_e32 vcc, v4, v3
	v_add_u32_e32 v4, 1, v6
	s_nop 0
	v_cndmask_b32_e32 v0, v0, v5, vcc
	v_mul_lo_u32 v5, v3, v0
	v_add_u32_e32 v3, v5, v3
	v_cmp_ne_u32_e32 vcc, v4, v3
	s_and_saveexec_b64 s[14:15], vcc
	s_xor_b64 s[16:17], exec, s[14:15]
	s_cbranch_execz .LBB0_286
	s_movk_i32 s66, 0xd40
	s_lshl_b64 s[14:15], s[66:67], 2
	s_add_u32 s22, s2, s14
	s_addc_u32 s23, s7, s15
	s_waitcnt lgkmcnt(0)
	global_load_dword v2, v1, s[22:23] sc1
	s_waitcnt vmcnt(0)
	v_cmp_eq_u32_e32 vcc, v2, v0
	s_and_saveexec_b64 s[18:19], vcc
	s_cbranch_execz .LBB0_285
	s_add_u32 s20, s10, 0x80200
	s_addc_u32 s21, s11, 0
	s_mov_b32 s13, 1
	s_mov_b64 s[24:25], 0
	s_branch .LBB0_276

.LBB0_597:
	s_or_b64 exec, exec, s[10:11]
	v_cvt_f32_u32_e32 v5, v3
	s_waitcnt vmcnt(0)
	v_readfirstlane_b32 s8, v4
	v_sub_u32_e32 v4, 0, v3
	v_rcp_iflag_f32_e32 v5, v5
	v_add_u32_e32 v6, s8, v0
	v_mul_f32_e32 v5, 0x4f7ffffe, v5
	v_cvt_u32_f32_e32 v5, v5
	v_mul_lo_u32 v0, v4, v5
	v_mul_hi_u32 v0, v5, v0
	v_add_u32_e32 v0, v5, v0
	v_mul_hi_u32 v0, v6, v0
	v_mul_lo_u32 v4, v0, v3
	v_sub_u32_e32 v4, v6, v4
	v_add_u32_e32 v5, 1, v0
	v_cmp_ge_u32_e32 vcc, v4, v3
	s_nop 1
	v_cndmask_b32_e32 v0, v0, v5, vcc
	v_sub_u32_e32 v5, v4, v3
	v_cndmask_b32_e32 v4, v4, v5, vcc
	v_add_u32_e32 v5, 1, v0
	v_cmp_ge_u32_e32 vcc, v4, v3
	v_add_u32_e32 v4, 1, v6
	s_nop 0
	v_cndmask_b32_e32 v0, v0, v5, vcc
	v_mul_lo_u32 v5, v3, v0
	v_add_u32_e32 v3, v5, v3
	v_cmp_ne_u32_e32 vcc, v4, v3
	s_and_saveexec_b64 s[8:9], vcc
	s_xor_b64 s[8:9], exec, s[8:9]
	s_cbranch_execz .LBB0_611
	s_movk_i32 s10, 0xd40
	s_mov_b32 s11, s67
	s_lshl_b64 s[10:11], s[10:11], 2
	s_add_u32 s18, s2, s10
	s_addc_u32 s19, s12, s11
	s_waitcnt lgkmcnt(0)
	global_load_dword v2, v1, s[18:19] sc1
	s_waitcnt vmcnt(0)
	v_cmp_eq_u32_e32 vcc, v2, v0
	s_and_saveexec_b64 s[10:11], vcc
	s_cbranch_execz .LBB0_610
	s_add_u32 s14, s6, 0x80200
	s_addc_u32 s15, s7, 0
	s_mov_b32 s16, 1
	s_mov_b64 s[20:21], 0
	s_branch .LBB0_601

.LBB0_662:
	s_or_b64 exec, exec, s[14:15]
	v_cvt_f32_u32_e32 v5, v3
	s_waitcnt vmcnt(0)
	v_readfirstlane_b32 s10, v4
	v_sub_u32_e32 v4, 0, v3
	v_rcp_iflag_f32_e32 v5, v5
	v_add_u32_e32 v6, s10, v0
	v_mul_f32_e32 v5, 0x4f7ffffe, v5
	v_cvt_u32_f32_e32 v5, v5
	v_mul_lo_u32 v0, v4, v5
	v_mul_hi_u32 v0, v5, v0
	v_add_u32_e32 v0, v5, v0
	v_mul_hi_u32 v0, v6, v0
	v_mul_lo_u32 v4, v0, v3
	v_sub_u32_e32 v4, v6, v4
	v_add_u32_e32 v5, 1, v0
	v_cmp_ge_u32_e32 vcc, v4, v3
	s_nop 1
	v_cndmask_b32_e32 v0, v0, v5, vcc
	v_sub_u32_e32 v5, v4, v3
	v_cndmask_b32_e32 v4, v4, v5, vcc
	v_add_u32_e32 v5, 1, v0
	v_cmp_ge_u32_e32 vcc, v4, v3
	v_add_u32_e32 v4, 1, v6
	s_nop 0
	v_cndmask_b32_e32 v0, v0, v5, vcc
	v_mul_lo_u32 v5, v3, v0
	v_add_u32_e32 v3, v5, v3
	v_cmp_ne_u32_e32 vcc, v4, v3
	s_and_saveexec_b64 s[10:11], vcc
	s_xor_b64 s[10:11], exec, s[10:11]
	s_cbranch_execz .LBB0_676
	s_movk_i32 s66, 0xd40
	s_lshl_b64 s[12:13], s[66:67], 2
	s_add_u32 s20, s2, s12
	s_addc_u32 s21, s4, s13
	s_waitcnt lgkmcnt(0)
	global_load_dword v2, v1, s[20:21] sc1
	s_waitcnt vmcnt(0)
	v_cmp_eq_u32_e32 vcc, v2, v0
	s_and_saveexec_b64 s[14:15], vcc
	s_cbranch_execz .LBB0_675
	s_add_u32 s18, s8, 0x80200
	s_addc_u32 s19, s9, 0
	s_mov_b32 s12, 1
	s_mov_b64 s[22:23], 0
	s_branch .LBB0_666

.LBB0_768:
	s_or_b64 exec, exec, s[14:15]
	v_cvt_f32_u32_e32 v5, v3
	s_waitcnt vmcnt(0)
	v_readfirstlane_b32 s10, v4
	v_sub_u32_e32 v4, 0, v3
	v_rcp_iflag_f32_e32 v5, v5
	v_add_u32_e32 v6, s10, v0
	v_mul_f32_e32 v5, 0x4f7ffffe, v5
	v_cvt_u32_f32_e32 v5, v5
	v_mul_lo_u32 v0, v4, v5
	v_mul_hi_u32 v0, v5, v0
	v_add_u32_e32 v0, v5, v0
	v_mul_hi_u32 v0, v6, v0
	v_mul_lo_u32 v4, v0, v3
	v_sub_u32_e32 v4, v6, v4
	v_add_u32_e32 v5, 1, v0
	v_cmp_ge_u32_e32 vcc, v4, v3
	s_nop 1
	v_cndmask_b32_e32 v0, v0, v5, vcc
	v_sub_u32_e32 v5, v4, v3
	v_cndmask_b32_e32 v4, v4, v5, vcc
	v_add_u32_e32 v5, 1, v0
	v_cmp_ge_u32_e32 vcc, v4, v3
	v_add_u32_e32 v4, 1, v6
	s_nop 0
	v_cndmask_b32_e32 v0, v0, v5, vcc
	v_mul_lo_u32 v5, v3, v0
	v_add_u32_e32 v3, v5, v3
	v_cmp_ne_u32_e32 vcc, v4, v3
	s_and_saveexec_b64 s[10:11], vcc
	s_xor_b64 s[10:11], exec, s[10:11]
	s_cbranch_execz .LBB0_782
	s_movk_i32 s66, 0xd40
	s_lshl_b64 s[12:13], s[66:67], 2
	s_add_u32 s18, s2, s12
	s_addc_u32 s19, s4, s13
	s_waitcnt lgkmcnt(0)
	global_load_dword v2, v1, s[18:19] sc1
	s_waitcnt vmcnt(0)
	v_cmp_eq_u32_e32 vcc, v2, v0
	s_and_saveexec_b64 s[14:15], vcc
	s_cbranch_execz .LBB0_781
	s_add_u32 s16, s8, 0x80200
	s_addc_u32 s17, s9, 0
	s_mov_b32 s12, 1
	s_mov_b64 s[20:21], 0
	s_branch .LBB0_772

.LBB0_1114:
	s_or_b64 exec, exec, s[12:13]
	v_cvt_f32_u32_e32 v5, v3
	s_waitcnt vmcnt(0)
	v_readfirstlane_b32 s10, v4
	v_sub_u32_e32 v4, 0, v3
	v_rcp_iflag_f32_e32 v5, v5
	v_add_u32_e32 v6, s10, v0
	v_mul_f32_e32 v5, 0x4f7ffffe, v5
	v_cvt_u32_f32_e32 v5, v5
	v_mul_lo_u32 v0, v4, v5
	v_mul_hi_u32 v0, v5, v0
	v_add_u32_e32 v0, v5, v0
	v_mul_hi_u32 v0, v6, v0
	v_mul_lo_u32 v4, v0, v3
	v_sub_u32_e32 v4, v6, v4
	v_add_u32_e32 v5, 1, v0
	v_cmp_ge_u32_e32 vcc, v4, v3
	s_nop 1
	v_cndmask_b32_e32 v0, v0, v5, vcc
	v_sub_u32_e32 v5, v4, v3
	v_cndmask_b32_e32 v4, v4, v5, vcc
	v_add_u32_e32 v5, 1, v0
	v_cmp_ge_u32_e32 vcc, v4, v3
	v_add_u32_e32 v4, 1, v6
	s_nop 0
	v_cndmask_b32_e32 v0, v0, v5, vcc
	v_mul_lo_u32 v5, v3, v0
	v_add_u32_e32 v3, v5, v3
	v_cmp_ne_u32_e32 vcc, v4, v3
	s_and_saveexec_b64 s[10:11], vcc
	s_xor_b64 s[10:11], exec, s[10:11]
	s_cbranch_execz .LBB0_1128
	s_movk_i32 s66, 0xd40
	s_lshl_b64 s[12:13], s[66:67], 2
	s_add_u32 s16, s2, s12
	s_addc_u32 s17, s4, s13
	s_waitcnt lgkmcnt(0)
	global_load_dword v2, v1, s[16:17] sc1
	s_waitcnt vmcnt(0)
	v_cmp_eq_u32_e32 vcc, v2, v0
	s_and_saveexec_b64 s[12:13], vcc
	s_cbranch_execz .LBB0_1127
	s_add_u32 s14, s8, 0x80200
	s_addc_u32 s15, s9, 0
	s_mov_b32 s28, 1
	s_mov_b64 s[18:19], 0
	s_branch .LBB0_1118

.LBB0_1234:
	s_or_b64 exec, exec, s[12:13]
	v_cvt_f32_u32_e32 v5, v3
	s_waitcnt vmcnt(0)
	v_readfirstlane_b32 s10, v4
	v_sub_u32_e32 v4, 0, v3
	v_rcp_iflag_f32_e32 v5, v5
	v_add_u32_e32 v6, s10, v0
	v_mul_f32_e32 v5, 0x4f7ffffe, v5
	v_cvt_u32_f32_e32 v5, v5
	v_mul_lo_u32 v0, v4, v5
	v_mul_hi_u32 v0, v5, v0
	v_add_u32_e32 v0, v5, v0
	v_mul_hi_u32 v0, v6, v0
	v_mul_lo_u32 v4, v0, v3
	v_sub_u32_e32 v4, v6, v4
	v_add_u32_e32 v5, 1, v0
	v_cmp_ge_u32_e32 vcc, v4, v3
	s_nop 1
	v_cndmask_b32_e32 v0, v0, v5, vcc
	v_sub_u32_e32 v5, v4, v3
	v_cndmask_b32_e32 v4, v4, v5, vcc
	v_add_u32_e32 v5, 1, v0
	v_cmp_ge_u32_e32 vcc, v4, v3
	v_add_u32_e32 v4, 1, v6
	s_nop 0
	v_cndmask_b32_e32 v0, v0, v5, vcc
	v_mul_lo_u32 v5, v3, v0
	v_add_u32_e32 v3, v5, v3
	v_cmp_ne_u32_e32 vcc, v4, v3
	s_and_saveexec_b64 s[10:11], vcc
	s_xor_b64 s[10:11], exec, s[10:11]
	s_cbranch_execz .LBB0_1248
	s_movk_i32 s12, 0xd40
	s_mov_b32 s13, s67
	s_lshl_b64 s[12:13], s[12:13], 2
	s_add_u32 s16, s2, s12
	s_addc_u32 s17, s4, s13
	s_waitcnt lgkmcnt(0)
	global_load_dword v2, v1, s[16:17] sc1
	s_waitcnt vmcnt(0)
	v_cmp_eq_u32_e32 vcc, v2, v0
	s_and_saveexec_b64 s[12:13], vcc
	s_cbranch_execz .LBB0_1247
	s_add_u32 s14, s8, 0x80200
	s_addc_u32 s15, s9, 0
	s_mov_b32 s28, 1
	s_mov_b64 s[18:19], 0
	s_branch .LBB0_1238

.LBB0_1293:
	s_or_b64 exec, exec, s[10:11]
	v_cvt_f32_u32_e32 v5, v3
	s_waitcnt vmcnt(0)
	v_readfirstlane_b32 s8, v4
	v_sub_u32_e32 v4, 0, v3
	v_rcp_iflag_f32_e32 v5, v5
	v_add_u32_e32 v6, s8, v0
	v_mul_f32_e32 v5, 0x4f7ffffe, v5
	v_cvt_u32_f32_e32 v5, v5
	v_mul_lo_u32 v0, v4, v5
	v_mul_hi_u32 v0, v5, v0
	v_add_u32_e32 v0, v5, v0
	v_mul_hi_u32 v0, v6, v0
	v_mul_lo_u32 v4, v0, v3
	v_sub_u32_e32 v4, v6, v4
	v_add_u32_e32 v5, 1, v0
	v_cmp_ge_u32_e32 vcc, v4, v3
	s_nop 1
	v_cndmask_b32_e32 v0, v0, v5, vcc
	v_sub_u32_e32 v5, v4, v3
	v_cndmask_b32_e32 v4, v4, v5, vcc
	v_add_u32_e32 v5, 1, v0
	v_cmp_ge_u32_e32 vcc, v4, v3
	v_add_u32_e32 v4, 1, v6
	s_nop 0
	v_cndmask_b32_e32 v0, v0, v5, vcc
	v_mul_lo_u32 v5, v3, v0
	v_add_u32_e32 v3, v5, v3
	v_cmp_ne_u32_e32 vcc, v4, v3
	s_and_saveexec_b64 s[8:9], vcc
	s_xor_b64 s[8:9], exec, s[8:9]
	s_cbranch_execz .LBB0_1307
	s_movk_i32 s66, 0xd40
	s_lshl_b64 s[10:11], s[66:67], 2
	s_add_u32 s14, s2, s10
	s_addc_u32 s15, s26, s11
	s_waitcnt lgkmcnt(0)
	global_load_dword v2, v1, s[14:15] sc1
	s_waitcnt vmcnt(0)
	v_cmp_eq_u32_e32 vcc, v2, v0
	s_and_saveexec_b64 s[10:11], vcc
	s_cbranch_execz .LBB0_1306
	s_add_u32 s12, s6, 0x80200
	s_addc_u32 s13, s7, 0
	s_mov_b32 s28, 1
	s_mov_b64 s[16:17], 0
	s_branch .LBB0_1297
